# attn_a: waves of the second half-block run the hand-written attention phase at static priority 1 (set once at phase entry, reset at exit); code addresses unchanged
# baseline (speedup 1.0000x reference)
; DI int t5_bucket(int dist) {
;   if (dist < 16) return dist;
;   float lp = logf((float)dist / 16.0f) / 4.852030263919617f * 16.0f;
;   int b = 16 + (int)lp;
;   return b < 31 ? b : 31;
; }
; DI void phase_attn_a(int wv_, int vb_, int nvb_, char* ws_, const Ctx& p, char* smem) {
;     ...
;   const int tid = tidx(wv_), lane = tid & 63, wave = tid >> 6, c = lane & 31, h = lane >> 5;
;   for (int k_ = 0; k_ < (6144 + nvb_ - 1) / nvb_; ++k_) {
;     const int u = (vb_ + k_ * nvb_ < 6144) ? vb_ + k_ * nvb_ : 6143;
;     const int head = u & 7, g = (u >> 3) % 3, rest = u / 24, idx = rest & 31, b = rest >> 5;
;     const int dil = (g == 0) ? 1 : ((g == 1) ? 4 : 16);
;     const int nbper = 32 / dil, r = idx / nbper, nb = idx % nbper;
;     u16* Og = (g == 0) ? (u16*)(ws_ + WS_H) : ((g == 1) ? (u16*)(ws_ + WS_H + 32 * MiB) : (u16*)(ws_ + WS_E));
;     float* lse = (float*)(ws_ + WS_LSE) + (size_t)g * NTOK * 8;
;     if (tid <= 128) sBias[tid] = p.rel_bias[t5_bucket(tid * dil) * 40 + g * 8 + head] * 1.4426950408889634f;
.LBB0_493:
	v_writelane_b32 v255, s54, 5
	s_cmp_lt_i32 s23, 2
	s_mov_b64 s[2:3], -1
	v_writelane_b32 v255, s55, 6
	s_cbranch_scc1 .LBB0_764
	s_cmp_gt_i32 s23, 2
	s_cbranch_scc0 .LBB0_552
	v_readlane_b32 s2, v253, 27
	v_readlane_b32 s3, v253, 28
	s_mov_b32 s0, s33
	v_mov_b32_e32 v0, v204
	s_andn2_b64 vcc, exec, s[2:3]
	s_cbranch_vccnz .LBB0_551
	s_mov_b32 s60, s33
	v_readlane_b32 s35, v253, 26
	v_readlane_b32 s44, v254, 14
	v_readlane_b32 s45, v254, 56
	v_readlane_b32 s56, v254, 32
	v_readlane_b32 s57, v254, 33
	s_bitcmp1_b32 s44, 0
	s_cbranch_scc0 .Lattn_pr
	s_setprio 1
.Lattn_pr:
	s_nop 0
	s_nop 0
	s_nop 0
	s_nop 0
	s_nop 0
	s_nop 0
	s_nop 0
	s_nop 0
	s_nop 0
	s_nop 0
	s_nop 0
	s_nop 0
	s_nop 0
	v_and_b32_e32 v196, 31, v204
	v_lshrrev_b32_e32 v197, 5, v204
	v_lshl_add_u32 v202, s60, 6, v204
	s_lshl_b32 s0, s60, 5
	v_add_u32_e32 v200, s0, v196
	v_lshlrev_b32_e32 v201, 4, v197
	v_lshlrev_b32_e32 v239, 3, v197
	v_lshrrev_b32_e32 v198, 3, v204
	v_lshl_add_u32 v199, s60, 6, v198
	v_add_u32_e32 v240, 0xffffff80, v199
	v_and_b32_e32 v246, 7, v204
	v_lshlrev_b32_e32 v241, 4, v246
	v_lshrrev_b32_e32 v247, 4, v204
	v_xor_b32_e32 v198, v246, v247
	v_lshlrev_b32_e32 v198, 4, v198
	v_lshl_add_u32 v203, v199, 7, v214
	v_add_u32_e32 v203, v203, v198
	v_xor_b32_e32 v198, 64, v198
	v_lshl_add_u32 v209, v199, 7, v214
	v_add_u32_e32 v209, v209, v198
	v_and_b32_e32 v247, 1, v247
	v_lshlrev_b32_e32 v247, 2, v247
	v_xor_b32_e32 v198, v246, v247
	v_lshlrev_b32_e32 v198, 4, v198
	v_lshl_add_u32 v216, v199, 7, v214
	v_add_u32_e32 v216, v216, v198
	v_add_u32_e32 v216, 0x8000, v216
	v_lshl_add_u32 v198, v200, 7, v214
	v_bfe_u32 v199, v196, 1, 3
	v_or_b32_e32 v246, 0, v197
	v_xor_b32_e32 v246, v246, v199
	v_lshl_add_u32 v217, v246, 4, v198
	v_or_b32_e32 v246, 2, v197
	v_xor_b32_e32 v246, v246, v199
	v_lshl_add_u32 v218, v246, 4, v198
	v_or_b32_e32 v246, 4, v197
	v_xor_b32_e32 v246, v246, v199
	v_lshl_add_u32 v219, v246, 4, v198
	v_or_b32_e32 v246, 6, v197
	v_xor_b32_e32 v246, v246, v199
	v_lshl_add_u32 v220, v246, 4, v198
	v_bfe_u32 v198, v196, 2, 2
	v_and_b32_e32 v199, 3, v196
	v_lshrrev_b32_e32 v246, 4, v196
	v_lshl_add_u32 v247, v197, 2, v198
	s_lshl_b32 s1, s60, 5
	v_add_u32_e32 v247, s1, v247
	v_lshl_add_u32 v247, v247, 7, v214
	v_add_u32_e32 v247, 0x8000, v247
	v_lshrrev_b32_e32 v198, 1, v198
	v_lshlrev_b32_e32 v246, 1, v246
	v_lshrrev_b32_e32 v236, 1, v199
	v_add_u32_e32 v246, v246, v236
	v_and_b32_e32 v199, 1, v199
	v_lshl_add_u32 v247, v199, 3, v247
	v_xor_b32_e32 v236, 0, v198
	v_lshl_add_u32 v236, v236, 2, v246
	v_lshl_add_u32 v221, v236, 4, v247
	v_xor_b32_e32 v236, 1, v198
	v_lshl_add_u32 v236, v236, 2, v246
	v_lshl_add_u32 v222, v236, 4, v247
	v_lshl_add_u32 v198, v196, 2, v214
	v_sub_u32_e32 v198, v198, v201
	v_add_u32_e32 v223, 0x10000, v198
	v_lshl_add_u32 v198, v202, 2, v214
	v_add_u32_e32 v224, 0x10000, v198
	v_add_u32_e32 v198, 0xffffffe1, v202
	v_cmp_gt_u32_e32 vcc, 0x81, v198
	s_mov_b64 s[66:67], vcc
	v_max_i32_e32 v198, 0, v198
	v_min_u32_e32 v198, 0x80, v198
	v_lshlrev_b32_e32 v199, 0, v198
	v_mov_b32_e32 v246, 16
	v_cmp_le_u32_e32 vcc, 22, v199
	s_nop 1
	v_addc_co_u32_e32 v246, vcc, 0, v246, vcc
	v_cmp_le_u32_e32 vcc, 30, v199
	s_nop 1
	v_addc_co_u32_e32 v246, vcc, 0, v246, vcc
	v_cmp_le_u32_e32 vcc, 40, v199
	s_nop 1
	v_addc_co_u32_e32 v246, vcc, 0, v246, vcc
	v_cmp_le_u32_e32 vcc, 54, v199
	s_nop 1
	v_addc_co_u32_e32 v246, vcc, 0, v246, vcc
	v_cmp_le_u32_e32 vcc, 0x49, v199
	s_nop 1
	v_addc_co_u32_e32 v246, vcc, 0, v246, vcc
	v_cmp_le_u32_e32 vcc, 0x63, v199
	s_nop 1
	v_addc_co_u32_e32 v246, vcc, 0, v246, vcc
	v_cmp_le_u32_e32 vcc, 0x86, v199
	s_nop 1
	v_addc_co_u32_e32 v246, vcc, 0, v246, vcc
	v_cmp_le_u32_e32 vcc, 0xb6, v199
	s_nop 1
	v_addc_co_u32_e32 v246, vcc, 0, v246, vcc
	v_cmp_le_u32_e32 vcc, 0xf6, v199
	s_nop 1
	v_addc_co_u32_e32 v246, vcc, 0, v246, vcc
	v_cmp_le_u32_e32 vcc, 0x14c, v199
	s_nop 1
	v_addc_co_u32_e32 v246, vcc, 0, v246, vcc
	v_cmp_le_u32_e32 vcc, 0x1c2, v199
	s_nop 1
; DI int t5_bucket(int dist) {
;   if (dist < 16) return dist;
;   float lp = logf((float)dist / 16.0f) / 4.852030263919617f * 16.0f;
;   int b = 16 + (int)lp;
;   return b < 31 ? b : 31;
; }
; DI void phase_attn_a(int wv_, int vb_, int nvb_, char* ws_, const Ctx& p, char* smem) {
;     ...
;   for (int k_ = 0; k_ < (6144 + nvb_ - 1) / nvb_; ++k_) {
;     const int u = (vb_ + k_ * nvb_ < 6144) ? vb_ + k_ * nvb_ : 6143;
;     const int head = u & 7, g = (u >> 3) % 3, rest = u / 24, idx = rest & 31, b = rest >> 5;
;     const int dil = (g == 0) ? 1 : ((g == 1) ? 4 : 16);
;     const int nbper = 32 / dil, r = idx / nbper, nb = idx % nbper;
	v_addc_co_u32_e32 v246, vcc, 0, v246, vcc
	v_cmp_le_u32_e32 vcc, 0x261, v199
	s_nop 1
	v_addc_co_u32_e32 v246, vcc, 0, v246, vcc
	v_cmp_le_u32_e32 vcc, 0x339, v199
	s_nop 1
	v_addc_co_u32_e32 v246, vcc, 0, v246, vcc
	v_cmp_le_u32_e32 vcc, 0x45d, v199
	s_nop 1
	v_addc_co_u32_e32 v246, vcc, 0, v246, vcc
	v_cmp_le_u32_e32 vcc, 0x5e9, v199
	s_nop 1
	v_addc_co_u32_e32 v246, vcc, 0, v246, vcc
	v_cmp_gt_u32_e32 vcc, 16, v199
	s_nop 1
	v_cndmask_b32_e32 v246, v246, v199, vcc
	v_mul_u32_u24_e32 v106, 0xa0, v246
	v_lshlrev_b32_e32 v199, 2, v198
	v_mov_b32_e32 v246, 16
	v_cmp_le_u32_e32 vcc, 22, v199
	s_nop 1
	v_addc_co_u32_e32 v246, vcc, 0, v246, vcc
	v_cmp_le_u32_e32 vcc, 30, v199
	s_nop 1
	v_addc_co_u32_e32 v246, vcc, 0, v246, vcc
	v_cmp_le_u32_e32 vcc, 40, v199
	s_nop 1
	v_addc_co_u32_e32 v246, vcc, 0, v246, vcc
	v_cmp_le_u32_e32 vcc, 54, v199
	s_nop 1
	v_addc_co_u32_e32 v246, vcc, 0, v246, vcc
	v_cmp_le_u32_e32 vcc, 0x49, v199
	s_nop 1
	v_addc_co_u32_e32 v246, vcc, 0, v246, vcc
	v_cmp_le_u32_e32 vcc, 0x63, v199
	s_nop 1
	v_addc_co_u32_e32 v246, vcc, 0, v246, vcc
	v_cmp_le_u32_e32 vcc, 0x86, v199
	s_nop 1
	v_addc_co_u32_e32 v246, vcc, 0, v246, vcc
	v_cmp_le_u32_e32 vcc, 0xb6, v199
	s_nop 1
	v_addc_co_u32_e32 v246, vcc, 0, v246, vcc
	v_cmp_le_u32_e32 vcc, 0xf6, v199
	s_nop 1
	v_addc_co_u32_e32 v246, vcc, 0, v246, vcc
	v_cmp_le_u32_e32 vcc, 0x14c, v199
	s_nop 1
	v_addc_co_u32_e32 v246, vcc, 0, v246, vcc
	v_cmp_le_u32_e32 vcc, 0x1c2, v199
	s_nop 1
	v_addc_co_u32_e32 v246, vcc, 0, v246, vcc
	v_cmp_le_u32_e32 vcc, 0x261, v199
	s_nop 1
	v_addc_co_u32_e32 v246, vcc, 0, v246, vcc
	v_cmp_le_u32_e32 vcc, 0x339, v199
	s_nop 1
	v_addc_co_u32_e32 v246, vcc, 0, v246, vcc
	v_cmp_le_u32_e32 vcc, 0x45d, v199
	s_nop 1
	v_addc_co_u32_e32 v246, vcc, 0, v246, vcc
	v_cmp_le_u32_e32 vcc, 0x5e9, v199
	s_nop 1
	v_addc_co_u32_e32 v246, vcc, 0, v246, vcc
	v_cmp_gt_u32_e32 vcc, 16, v199
	s_nop 1
	v_cndmask_b32_e32 v246, v246, v199, vcc
	v_mul_u32_u24_e32 v107, 0xa0, v246
	v_lshlrev_b32_e32 v199, 4, v198
	v_mov_b32_e32 v246, 16
	v_cmp_le_u32_e32 vcc, 22, v199
	s_nop 1
	v_addc_co_u32_e32 v246, vcc, 0, v246, vcc
	v_cmp_le_u32_e32 vcc, 30, v199
	s_nop 1
	v_addc_co_u32_e32 v246, vcc, 0, v246, vcc
	v_cmp_le_u32_e32 vcc, 40, v199
	s_nop 1
	v_addc_co_u32_e32 v246, vcc, 0, v246, vcc
	v_cmp_le_u32_e32 vcc, 54, v199
	s_nop 1
	v_addc_co_u32_e32 v246, vcc, 0, v246, vcc
	v_cmp_le_u32_e32 vcc, 0x49, v199
	s_nop 1
	v_addc_co_u32_e32 v246, vcc, 0, v246, vcc
	v_cmp_le_u32_e32 vcc, 0x63, v199
	s_nop 1
	v_addc_co_u32_e32 v246, vcc, 0, v246, vcc
	v_cmp_le_u32_e32 vcc, 0x86, v199
	s_nop 1
	v_addc_co_u32_e32 v246, vcc, 0, v246, vcc
	v_cmp_le_u32_e32 vcc, 0xb6, v199
	s_nop 1
	v_addc_co_u32_e32 v246, vcc, 0, v246, vcc
	v_cmp_le_u32_e32 vcc, 0xf6, v199
	s_nop 1
	v_addc_co_u32_e32 v246, vcc, 0, v246, vcc
	v_cmp_le_u32_e32 vcc, 0x14c, v199
	s_nop 1
	v_addc_co_u32_e32 v246, vcc, 0, v246, vcc
	v_cmp_le_u32_e32 vcc, 0x1c2, v199
	s_nop 1
	v_addc_co_u32_e32 v246, vcc, 0, v246, vcc
	v_cmp_le_u32_e32 vcc, 0x261, v199
	s_nop 1
	v_addc_co_u32_e32 v246, vcc, 0, v246, vcc
	v_cmp_le_u32_e32 vcc, 0x339, v199
	s_nop 1
	v_addc_co_u32_e32 v246, vcc, 0, v246, vcc
	v_cmp_le_u32_e32 vcc, 0x45d, v199
	s_nop 1
	v_addc_co_u32_e32 v246, vcc, 0, v246, vcc
	v_cmp_le_u32_e32 vcc, 0x5e9, v199
	s_nop 1
	v_addc_co_u32_e32 v246, vcc, 0, v246, vcc
	v_cmp_gt_u32_e32 vcc, 16, v199
	s_nop 1
	v_cndmask_b32_e32 v246, v246, v199, vcc
	v_mul_u32_u24_e32 v108, 0xa0, v246
	s_mov_b32 s0, 0
	s_cmp_eq_u32 s45, 0x200
	s_cbranch_scc0 .Lattn_map_old1
	s_lshr_b32 s1, s44, 1
	s_and_b32 s3, s1, 7
	s_lshr_b32 s1, s1, 3
	s_and_b32 s63, s0, 3
	s_lshl_b32 s63, s63, 3
	s_lshr_b32 s68, s1, 3
	s_lshl_b32 s68, s68, 1
	s_add_i32 s63, s63, s68
	s_and_b32 s68, s44, 1
	s_add_i32 s63, s63, s68
	s_lshl_b32 s3, s3, 5
	s_add_i32 s63, s63, s3
	s_mul_i32 s63, s63, 3
	s_lshr_b32 s68, s0, 2
	s_min_u32 s68, s68, 2
	s_add_i32 s63, s63, s68
	s_and_b32 s1, s1, 7
	s_lshl_b32 s0, s63, 3
	s_or_b32 s0, s0, s1
	s_branch .Lattn_map_done1

; DI float shx(float v, int m) { return __int_as_float(__builtin_amdgcn_ds_bpermute((lane_now() ^ m) << 2, __float_as_int(v))); }
; DI int shx(int v, int m) { return __builtin_amdgcn_ds_bpermute((lane_now() ^ m) << 2, v); }
; DI u16 f2bf(float x) { return (u16)(pk2bf(x, 0.f) & 0xffffu); }
; DI void phase_attn_a(int wv_, int vb_, int nvb_, char* ws_, const Ctx& p, char* smem) {
;     ...
;       sum += shx(sum, 32);
;       const float inv = 1.0f / sum;
;       u16* op = Og + ((size_t)b * SEQ + qtok) * 512 + head * 64;
; #pragma unroll
;       for (int mb = 0; mb < 2; ++mb)
; #pragma unroll
;         for (int ig = 0; ig < 4; ++ig) {
;           s16x4 o;
; #pragma unroll
;           for (int q = 0; q < 4; ++q) o[q] = (short)f2bf(oacc[mb][ig * 4 + q] * inv);
;           *(s16x4*)(op + mb * 32 + 8 * ig + 4 * h) = o;
;         }
;       if (h == 0) lse[((size_t)b * SEQ + qtok) * 8 + head] = (mx + log2f(sum)) * 0.6931471805599453f;
;     }
;     __syncthreads();
.Lattn_end4:
	s_nop 7
	s_nop 7
	v_mov_b32_e32 v196, v195
	s_nop 1
	v_permlane32_swap_b32_e32 v196, v195
	v_add_f32_e32 v195, v195, v196
	v_rcp_f32_e32 v238, v195
	v_log_f32_e32 v197, v195
	s_nop 0
	v_mul_f32_e32 v146, v238, v146
	v_mul_f32_e32 v147, v238, v147
	v_mul_f32_e32 v148, v238, v148
	v_mul_f32_e32 v149, v238, v149
	v_mul_f32_e32 v150, v238, v150
	v_mul_f32_e32 v151, v238, v151
	v_mul_f32_e32 v152, v238, v152
	v_mul_f32_e32 v153, v238, v153
	v_mul_f32_e32 v154, v238, v154
	v_mul_f32_e32 v155, v238, v155
	v_mul_f32_e32 v156, v238, v156
	v_mul_f32_e32 v157, v238, v157
	v_mul_f32_e32 v158, v238, v158
	v_mul_f32_e32 v159, v238, v159
	v_mul_f32_e32 v160, v238, v160
	v_mul_f32_e32 v161, v238, v161
	v_mul_f32_e32 v162, v238, v162
	v_mul_f32_e32 v163, v238, v163
	v_mul_f32_e32 v164, v238, v164
	v_mul_f32_e32 v165, v238, v165
	v_mul_f32_e32 v166, v238, v166
	v_mul_f32_e32 v167, v238, v167
	v_mul_f32_e32 v168, v238, v168
	v_mul_f32_e32 v169, v238, v169
	v_mul_f32_e32 v170, v238, v170
	v_mul_f32_e32 v171, v238, v171
	v_mul_f32_e32 v172, v238, v172
	v_mul_f32_e32 v173, v238, v173
	v_mul_f32_e32 v174, v238, v174
	v_mul_f32_e32 v175, v238, v175
	v_mul_f32_e32 v176, v238, v176
	v_mul_f32_e32 v177, v238, v177
	v_cvt_pk_bf16_f32 v146, v146, v147
	v_cvt_pk_bf16_f32 v147, v148, v149
	v_cvt_pk_bf16_f32 v150, v150, v151
	v_cvt_pk_bf16_f32 v151, v152, v153
	v_cvt_pk_bf16_f32 v154, v154, v155
	v_cvt_pk_bf16_f32 v155, v156, v157
	v_cvt_pk_bf16_f32 v158, v158, v159
	v_cvt_pk_bf16_f32 v159, v160, v161
	v_cvt_pk_bf16_f32 v162, v162, v163
	v_cvt_pk_bf16_f32 v163, v164, v165
	v_cvt_pk_bf16_f32 v166, v166, v167
	v_cvt_pk_bf16_f32 v167, v168, v169
	v_cvt_pk_bf16_f32 v170, v170, v171
	v_cvt_pk_bf16_f32 v171, v172, v173
	v_cvt_pk_bf16_f32 v174, v174, v175
	v_cvt_pk_bf16_f32 v175, v176, v177
	global_store_dwordx2 v225, v[146:147], s[4:5]
	global_store_dwordx2 v225, v[150:151], s[4:5] offset:16
	global_store_dwordx2 v225, v[154:155], s[4:5] offset:32
	global_store_dwordx2 v225, v[158:159], s[4:5] offset:48
	global_store_dwordx2 v225, v[162:163], s[4:5] offset:64
	global_store_dwordx2 v225, v[166:167], s[4:5] offset:80
	global_store_dwordx2 v225, v[170:171], s[4:5] offset:96
	global_store_dwordx2 v225, v[174:175], s[4:5] offset:112
	v_add_f32_e32 v197, v194, v197
	v_mul_f32_e32 v197, 0x3f317218, v197
	s_mov_b32 exec_hi, 0
	global_store_dword v227, v197, s[6:7]
	s_mov_b32 exec_hi, -1
	s_add_i32 s34, s34, 1
	s_cmp_lt_i32 s34, s35
	s_cbranch_scc1 .Lattn_loop
	s_waitcnt vmcnt(0)
	s_barrier
	s_setprio 0
	s_nop 0
	s_nop 0
	s_nop 0
	s_nop 0
	s_nop 0
	s_nop 0
	s_nop 0
	s_nop 0
	s_nop 0
	s_nop 0
	s_nop 0
	s_nop 0
	s_nop 0
	s_nop 0
	s_nop 0
